# P62: row-statistic xor-16 sums in the GEMM epilogues via v_permlane16_swap instead of ds_swizzle + wait (25 chains), on top of P58 + P60
# speedup vs baseline: 1.0100x; 1.0100x over previous
.LBB0_479:
	s_andn2_b64 vcc, exec, s[14:15]
	s_cmp_lg_u32 s9, 0
	s_cselect_b64 s[52:53], -1, 0
	s_lshl_b64 s[10:11], s[10:11], 2
	s_add_u32 s10, s47, s10
	s_addc_u32 s11, s90, s11
	s_lshl_b32 s16, s8, 8
	s_add_i32 s16, s16, s88
	v_or_b32_e32 v200, s16, v208
	v_ashrrev_i32_e32 v201, 31, v200
	v_lshlrev_b64 v[4:5], 6, v[200:201]
	v_lshl_add_u64 v[24:25], v[184:185], 0, v[4:5]
	global_load_dwordx4 v[4:7], v[24:25], off
	v_or_b32_e32 v198, 16, v200
	v_ashrrev_i32_e32 v199, 31, v198
	v_lshlrev_b64 v[8:9], 6, v[198:199]
	v_lshl_add_u64 v[8:9], v[184:185], 0, v[8:9]
	global_load_dwordx4 v[8:11], v[8:9], off
	v_or_b32_e32 v196, 32, v200
	v_ashrrev_i32_e32 v197, 31, v196
	v_lshlrev_b64 v[12:13], 6, v[196:197]
	v_lshl_add_u64 v[12:13], v[184:185], 0, v[12:13]
	global_load_dwordx4 v[12:15], v[12:13], off
	v_or_b32_e32 v194, 48, v200
	v_ashrrev_i32_e32 v195, 31, v194
	v_lshlrev_b64 v[16:17], 6, v[194:195]
	v_lshl_add_u64 v[16:17], v[184:185], 0, v[16:17]
	global_load_dwordx4 v[16:19], v[16:17], off
	v_add_u32_e32 v192, 0x80, v200
	v_ashrrev_i32_e32 v193, 31, v192
	v_lshlrev_b64 v[20:21], 6, v[192:193]
	v_lshl_add_u64 v[20:21], v[184:185], 0, v[20:21]
	global_load_dwordx4 v[20:23], v[20:21], off
	v_add_co_u32_e32 v32, vcc, s59, v24
	v_lshl_add_u32 v190, s12, 8, v210
	s_nop 0
	v_addc_co_u32_e32 v33, vcc, 0, v25, vcc
	global_load_dwordx4 v[24:27], v[32:33], off offset:1024
	global_load_dwordx4 v[28:31], v[32:33], off offset:2048
	global_load_dwordx4 v[66:69], v[32:33], off offset:3072
	v_ashrrev_i32_e32 v191, 31, v190
	v_lshl_add_u64 v[2:3], v[190:191], 2, s[10:11]
	s_and_b64 s[10:11], s[6:7], s[52:53]
	s_andn2_b64 vcc, exec, s[10:11]
	s_waitcnt vmcnt(0)
	v_add_f32_e32 v4, v4, v5
	v_add_f32_e32 v5, v6, v7
	v_add_f32_e32 v4, v4, v5
	s_waitcnt lgkmcnt(0)
	v_mov_b32_e32 v5, v4
	s_nop 1
	v_permlane16_swap_b32_e32 v4, v5
	v_add_f32_e32 v197, v4, v5
	v_add_f32_e32 v4, v8, v9
	v_add_f32_e32 v5, v10, v11
	v_add_f32_e32 v4, v4, v5
	v_mov_b32_e32 v202, v197
	s_nop 1
	v_permlane32_swap_b32_e32 v197, v202
	s_waitcnt lgkmcnt(0)
	v_mov_b32_e32 v5, v4
	s_nop 1
	v_permlane16_swap_b32_e32 v4, v5
	v_add_f32_e32 v224, v4, v5
	v_add_f32_e32 v4, v12, v13
	v_add_f32_e32 v5, v14, v15
	v_add_f32_e32 v4, v4, v5
	v_mov_b32_e32 v225, v224
	s_nop 1
	v_permlane32_swap_b32_e32 v224, v225
	s_waitcnt lgkmcnt(0)
	v_mov_b32_e32 v5, v4
	s_nop 1
	v_permlane16_swap_b32_e32 v4, v5
	v_add_f32_e32 v222, v4, v5
	v_add_f32_e32 v4, v16, v17
	v_add_f32_e32 v5, v18, v19
	v_add_f32_e32 v4, v4, v5
	v_mov_b32_e32 v223, v222
	s_nop 1
	v_permlane32_swap_b32_e32 v222, v223
	s_waitcnt lgkmcnt(0)
	v_mov_b32_e32 v5, v4
	s_nop 1
	v_permlane16_swap_b32_e32 v4, v5
	v_add_f32_e32 v220, v4, v5
	v_add_f32_e32 v4, v20, v21
	v_add_f32_e32 v5, v22, v23
	v_add_f32_e32 v4, v4, v5
	v_mov_b32_e32 v221, v220
	s_nop 1
	v_permlane32_swap_b32_e32 v220, v221
	s_waitcnt lgkmcnt(0)
	v_mov_b32_e32 v5, v4
	s_nop 1
	v_permlane16_swap_b32_e32 v4, v5
	v_add_f32_e32 v218, v4, v5
	v_add_f32_e32 v4, v24, v25
	v_add_f32_e32 v5, v26, v27
	v_add_f32_e32 v4, v4, v5
	v_mov_b32_e32 v219, v218
	s_nop 1
	v_permlane32_swap_b32_e32 v218, v219
	s_waitcnt lgkmcnt(0)
	v_mov_b32_e32 v5, v4
	s_nop 1
	v_permlane16_swap_b32_e32 v4, v5
	v_add_f32_e32 v216, v4, v5
	v_add_f32_e32 v4, v28, v29
	v_add_f32_e32 v5, v30, v31
	v_add_f32_e32 v4, v4, v5
	v_mov_b32_e32 v217, v216
	s_nop 1
	v_permlane32_swap_b32_e32 v216, v217
	s_waitcnt lgkmcnt(0)
	v_mov_b32_e32 v5, v4
	s_nop 1
	v_permlane16_swap_b32_e32 v4, v5
	v_add_f32_e32 v199, v4, v5
	v_add_f32_e32 v4, v66, v67
	v_add_f32_e32 v5, v68, v69
	global_load_dwordx4 v[82:85], v[2:3], off offset:16
	global_load_dwordx4 v[86:89], v[2:3], off
	global_load_dwordx4 v[66:69], v[2:3], off offset:528
	global_load_dwordx4 v[70:73], v[2:3], off offset:512
	v_add_f32_e32 v4, v4, v5
	ds_swizzle_b32 v5, v4 offset:swizzle(SWAP,16)
	v_mov_b32_e32 v201, v199
	v_cndmask_b32_e64 v2, 0, 1, s[10:11]
	s_nop 0
	v_permlane32_swap_b32_e32 v199, v201
	s_waitcnt lgkmcnt(0)
	v_add_f32_e32 v193, v4, v5
	v_mov_b32_e32 v195, v193
	s_nop 1
	v_permlane32_swap_b32_e32 v193, v195
	v_cmp_ne_u32_e64 s[14:15], 1, v2
	s_cbranch_vccnz .LBB0_481
	s_bfe_u32 s8, s16, 0x50006
	v_mov_b32_e32 v2, s8
	v_cndmask_b32_e64 v2, v208, v2, s[2:3]
	v_lshlrev_b32_e32 v3, 2, v211
	v_lshl_or_b32 v2, v2, 7, v3
	v_add_u32_e32 v2, 0x24000, v2
	ds_read_b128 v[14:17], v2 offset:48
	ds_read_b128 v[10:13], v2 offset:32
	ds_read_b128 v[6:9], v2 offset:16
	s_nop 0
	ds_read_b128 v[2:5], v2

.LBB0_1253:
	v_lshl_add_u32 v184, s36, 8, v167
	v_ashrrev_i32_e32 v185, 31, v184
	v_or_b32_e32 v180, 16, v184
	v_lshlrev_b64 v[130:131], 6, v[184:185]
	v_ashrrev_i32_e32 v181, 31, v180
	v_or_b32_e32 v176, 32, v184
	v_lshl_add_u64 v[130:131], v[154:155], 0, v[130:131]
	v_lshlrev_b64 v[132:133], 6, v[180:181]
	v_ashrrev_i32_e32 v177, 31, v176
	v_lshl_add_u64 v[132:133], v[154:155], 0, v[132:133]
	global_load_dwordx4 v[186:189], v[130:131], off
	global_load_dwordx4 v[190:193], v[132:133], off
	v_lshlrev_b64 v[130:131], 6, v[176:177]
	v_lshl_add_u64 v[130:131], v[154:155], 0, v[130:131]
	global_load_dwordx4 v[194:197], v[130:131], off
	v_or_b32_e32 v172, 48, v184
	v_ashrrev_i32_e32 v173, 31, v172
	v_lshlrev_b64 v[130:131], 6, v[172:173]
	v_lshl_add_u64 v[130:131], v[154:155], 0, v[130:131]
	global_load_dwordx4 v[198:201], v[130:131], off
	v_add_u32_e32 v168, 0x80, v184
	v_ashrrev_i32_e32 v169, 31, v168
	v_lshlrev_b64 v[130:131], 6, v[168:169]
	v_lshl_add_u64 v[130:131], v[154:155], 0, v[130:131]
	global_load_dwordx4 v[202:205], v[130:131], off
	v_add_u32_e32 v164, 0x90, v184
	v_ashrrev_i32_e32 v165, 31, v164
	v_lshlrev_b64 v[130:131], 6, v[164:165]
	v_lshl_add_u64 v[130:131], v[154:155], 0, v[130:131]
	global_load_dwordx4 v[206:209], v[130:131], off
	v_add_u32_e32 v162, 0xa0, v184
	v_add_u32_e32 v160, 0xb0, v184
	v_ashrrev_i32_e32 v163, 31, v162
	s_lshl_b64 s[20:21], s[20:21], 2
	v_ashrrev_i32_e32 v161, 31, v160
	v_lshlrev_b64 v[130:131], 6, v[162:163]
	s_add_u32 s11, s38, s20
	v_lshlrev_b64 v[132:133], 6, v[160:161]
	v_lshl_add_u64 v[130:131], v[154:155], 0, v[130:131]
	s_addc_u32 s13, s39, s21
	s_lshl_b32 s20, s18, 8
	v_lshl_add_u64 v[132:133], v[154:155], 0, v[132:133]
	global_load_dwordx4 v[210:213], v[130:131], off
	global_load_dwordx4 v[214:217], v[132:133], off
	s_ashr_i32 s21, s20, 31
	s_lshl_b64 s[20:21], s[20:21], 2
	s_add_u32 s11, s11, s20
	s_addc_u32 s13, s13, s21
	s_lshl_b32 s19, s40, 2
	s_add_u32 s20, s11, s19
	s_addc_u32 s21, s13, 0
	v_lshl_add_u64 v[138:139], v[152:153], 2, s[20:21]
	global_load_dwordx4 v[134:137], v[138:139], off offset:16
	global_load_dwordx4 v[142:145], v[138:139], off
	global_load_dwordx4 v[130:133], v[138:139], off offset:528
	s_nop 0
	global_load_dwordx4 v[138:141], v[138:139], off offset:512
	s_lshl_b32 s18, s18, 7
	s_ashr_i32 s19, s18, 31
	s_lshl_b64 s[18:19], s[18:19], 1
	s_lshl_b32 s36, s40, 1
	s_andn2_b64 vcc, exec, s[8:9]
	s_mov_b64 s[8:9], -1
	s_waitcnt vmcnt(0)
	v_mov_b32_e32 v178, v187
	v_mov_b32_e32 v179, v188
	v_mov_b32_e32 v187, v189
	v_pk_add_f32 v[178:179], v[178:179], v[186:187]
	v_mov_b32_e32 v182, v191
	v_mov_b32_e32 v183, v192
	v_mov_b32_e32 v191, v193
	v_mov_b32_e32 v186, v195
	v_mov_b32_e32 v187, v196
	v_mov_b32_e32 v195, v197
	v_add_f32_e32 v161, v178, v179
	v_pk_add_f32 v[178:179], v[182:183], v[190:191]
	v_pk_add_f32 v[182:183], v[186:187], v[194:195]
	ds_swizzle_b32 v163, v161 offset:swizzle(SWAP,16)
	v_add_f32_e32 v165, v178, v179
	v_add_f32_e32 v166, v182, v183
	ds_swizzle_b32 v170, v165 offset:swizzle(SWAP,16)
	ds_swizzle_b32 v173, v166 offset:swizzle(SWAP,16)
	v_mov_b32_e32 v188, v199
	v_mov_b32_e32 v189, v200
	v_mov_b32_e32 v199, v201
	v_pk_add_f32 v[186:187], v[188:189], v[198:199]
	s_waitcnt lgkmcnt(2)
	v_add_f32_e32 v161, v161, v163
	v_add_f32_e32 v169, v186, v187
	v_mov_b32_e32 v163, v161
	s_waitcnt lgkmcnt(1)
	v_add_f32_e32 v165, v165, v170
	ds_swizzle_b32 v174, v169 offset:swizzle(SWAP,16)
	s_waitcnt lgkmcnt(1)
	v_add_f32_e32 v166, v166, v173
	v_permlane32_swap_b32_e32 v161, v163
	v_mov_b32_e32 v170, v165
	v_mov_b32_e32 v173, v166
	v_add_f32_e32 v161, v161, v163
	v_permlane32_swap_b32_e32 v165, v170
	v_permlane32_swap_b32_e32 v166, v173
	v_fmamk_f32 v161, v161, 0x3a800000, v244
	v_add_f32_e32 v163, v165, v170
	v_mov_b32_e32 v178, v203
	v_mov_b32_e32 v179, v204
	v_mov_b32_e32 v203, v205
	v_add_f32_e32 v165, v166, v173
	v_rsq_f32_e32 v190, v161
	v_fmamk_f32 v161, v163, 0x3a800000, v244
	v_pk_add_f32 v[178:179], v[178:179], v[202:203]
	v_rsq_f32_e32 v188, v161
	v_fmamk_f32 v161, v165, 0x3a800000, v244
	v_add_f32_e32 v165, v178, v179
	v_rsq_f32_e32 v186, v161
	s_waitcnt lgkmcnt(0)
	v_add_f32_e32 v161, v169, v174
	v_mov_b32_e32 v163, v161
	s_nop 1
	v_permlane32_swap_b32_e32 v161, v163
	v_add_f32_e32 v161, v161, v163
	v_mov_b32_e32 v178, v207
	v_mov_b32_e32 v179, v208
	v_mov_b32_e32 v207, v209
	v_fmamk_f32 v161, v161, 0x3a800000, v244
	v_pk_add_f32 v[178:179], v[178:179], v[206:207]
	v_rsq_f32_e32 v182, v161
	s_waitcnt lgkmcnt(0)
	v_mov_b32_e32 v166, v165
	s_nop 1
	v_permlane16_swap_b32_e32 v165, v166
	v_add_f32_e32 v161, v165, v166
	v_add_f32_e32 v165, v178, v179
	v_mov_b32_e32 v163, v161
	s_nop 1
	v_permlane32_swap_b32_e32 v161, v163
	v_add_f32_e32 v161, v161, v163
	v_mov_b32_e32 v192, v211
	v_mov_b32_e32 v193, v212
	v_mov_b32_e32 v211, v213
	v_fmamk_f32 v161, v161, 0x3a800000, v244
	v_pk_add_f32 v[192:193], v[192:193], v[210:211]
	v_rsq_f32_e32 v178, v161
	s_waitcnt lgkmcnt(0)
	v_mov_b32_e32 v166, v165
	s_nop 1
	v_permlane16_swap_b32_e32 v165, v166
	v_add_f32_e32 v161, v165, v166
	v_add_f32_e32 v165, v192, v193
	v_mov_b32_e32 v163, v161
	s_nop 1
	v_permlane32_swap_b32_e32 v161, v163
	v_add_f32_e32 v161, v161, v163
	v_mov_b32_e32 v192, v215
	v_mov_b32_e32 v193, v216
	v_mov_b32_e32 v215, v217
	v_fmamk_f32 v161, v161, 0x3a800000, v244
	v_pk_add_f32 v[192:193], v[192:193], v[214:215]
	v_pk_fma_f32 v[126:127], v[126:127], v[190:191], v[142:143] op_sel_hi:[1,0,1]
	v_rsq_f32_e32 v174, v161
	s_waitcnt lgkmcnt(0)
	v_mov_b32_e32 v166, v165
	s_nop 1
	v_permlane16_swap_b32_e32 v165, v166
	v_add_f32_e32 v161, v165, v166
	v_add_f32_e32 v165, v192, v193
	v_pk_mul_f32 v[192:193], v[126:127], s[84:85] op_sel_hi:[1,0]
	v_pk_fma_f32 v[128:129], v[128:129], v[190:191], v[144:145] op_sel_hi:[1,0,1]
	v_exp_f32_e32 v192, v192
	v_exp_f32_e32 v193, v193
	v_pk_mul_f32 v[194:195], v[128:129], s[84:85] op_sel_hi:[1,0]
	v_pk_fma_f32 v[118:119], v[118:119], v[190:191], v[138:139] op_sel_hi:[1,0,1]
	v_exp_f32_e32 v194, v194
	v_pk_add_f32 v[192:193], v[192:193], 1.0 op_sel_hi:[1,0]
	v_exp_f32_e32 v195, v195
	v_rcp_f32_e32 v192, v192
	v_rcp_f32_e32 v193, v193
	v_pk_fma_f32 v[122:123], v[122:123], v[190:191], v[134:135] op_sel_hi:[1,0,1]
	v_pk_fma_f32 v[120:121], v[120:121], v[190:191], v[140:141] op_sel_hi:[1,0,1]
	v_pk_fma_f32 v[124:125], v[124:125], v[190:191], v[136:137] op_sel_hi:[1,0,1]
	v_pk_mul_f32 v[126:127], v[126:127], v[192:193]
	v_pk_mul_f32 v[192:193], v[122:123], s[84:85] op_sel_hi:[1,0]
	v_pk_mul_f32 v[118:119], v[118:119], v[126:127]
	v_pk_add_f32 v[126:127], v[194:195], 1.0 op_sel_hi:[1,0]
	v_exp_f32_e32 v192, v192
	v_rcp_f32_e32 v126, v126
	v_rcp_f32_e32 v127, v127
	v_exp_f32_e32 v193, v193
	v_cvt_pk_bf16_f32 v118, v118, v119
	v_pk_fma_f32 v[114:115], v[114:115], v[190:191], v[130:131] op_sel_hi:[1,0,1]
	v_pk_mul_f32 v[126:127], v[128:129], v[126:127]
	v_pk_mul_f32 v[128:129], v[124:125], s[84:85] op_sel_hi:[1,0]
	v_pk_mul_f32 v[120:121], v[120:121], v[126:127]
	v_pk_add_f32 v[126:127], v[192:193], 1.0 op_sel_hi:[1,0]
	v_exp_f32_e32 v128, v128
	v_rcp_f32_e32 v126, v126
	v_rcp_f32_e32 v127, v127
	v_exp_f32_e32 v129, v129
	v_cvt_pk_bf16_f32 v119, v120, v121
	v_pk_fma_f32 v[110:111], v[110:111], v[188:189], v[142:143] op_sel_hi:[1,0,1]
	v_pk_mul_f32 v[120:121], v[122:123], v[126:127]
	v_pk_add_f32 v[122:123], v[128:129], 1.0 op_sel_hi:[1,0]
	v_pk_mul_f32 v[114:115], v[114:115], v[120:121]
	v_rcp_f32_e32 v122, v122
	v_rcp_f32_e32 v123, v123
	v_cvt_pk_bf16_f32 v120, v114, v115
	v_pk_fma_f32 v[114:115], v[116:117], v[190:191], v[132:133] op_sel_hi:[1,0,1]
	v_pk_fma_f32 v[112:113], v[112:113], v[188:189], v[144:145] op_sel_hi:[1,0,1]
	v_pk_mul_f32 v[116:117], v[124:125], v[122:123]
	v_pk_mul_f32 v[124:125], v[110:111], s[84:85] op_sel_hi:[1,0]
	v_pk_mul_f32 v[114:115], v[114:115], v[116:117]
	v_exp_f32_e32 v124, v124
	v_cvt_pk_bf16_f32 v121, v114, v115
	v_mov_b64_e32 v[114:115], s[4:5]
	v_mad_i64_i32 v[116:117], s[20:21], v184, s72, v[114:115]
	v_exp_f32_e32 v125, v125
	v_lshl_add_u64 v[116:117], v[116:117], 0, s[18:19]
	v_lshl_add_u64 v[122:123], v[116:117], 0, s[36:37]
	v_lshlrev_b64 v[116:117], 1, v[152:153]
	v_lshl_add_u64 v[122:123], v[122:123], 0, v[116:117]
	global_store_dwordx4 v[122:123], v[118:121], off
	v_pk_fma_f32 v[102:103], v[102:103], v[188:189], v[138:139] op_sel_hi:[1,0,1]
	v_pk_fma_f32 v[106:107], v[106:107], v[188:189], v[134:135] op_sel_hi:[1,0,1]
	v_pk_add_f32 v[118:119], v[124:125], 1.0 op_sel_hi:[1,0]
	v_pk_mul_f32 v[120:121], v[112:113], s[84:85] op_sel_hi:[1,0]
	v_rcp_f32_e32 v118, v118
	v_rcp_f32_e32 v119, v119
	v_exp_f32_e32 v120, v120
	v_exp_f32_e32 v121, v121
	v_pk_fma_f32 v[104:105], v[104:105], v[188:189], v[140:141] op_sel_hi:[1,0,1]
	v_pk_mul_f32 v[110:111], v[110:111], v[118:119]
	v_pk_mul_f32 v[118:119], v[106:107], s[84:85] op_sel_hi:[1,0]
	v_pk_mul_f32 v[102:103], v[102:103], v[110:111]
	v_pk_add_f32 v[110:111], v[120:121], 1.0 op_sel_hi:[1,0]
	v_exp_f32_e32 v118, v118
	v_rcp_f32_e32 v110, v110
	v_rcp_f32_e32 v111, v111
	v_exp_f32_e32 v119, v119
	v_pk_fma_f32 v[108:109], v[108:109], v[188:189], v[136:137] op_sel_hi:[1,0,1]
	v_cvt_pk_bf16_f32 v102, v102, v103
	v_pk_mul_f32 v[110:111], v[112:113], v[110:111]
	v_pk_mul_f32 v[112:113], v[108:109], s[84:85] op_sel_hi:[1,0]
	v_pk_mul_f32 v[104:105], v[104:105], v[110:111]
	v_pk_add_f32 v[110:111], v[118:119], 1.0 op_sel_hi:[1,0]
	v_exp_f32_e32 v112, v112
	v_rcp_f32_e32 v110, v110
	v_rcp_f32_e32 v111, v111
	v_exp_f32_e32 v113, v113
	v_cvt_pk_bf16_f32 v103, v104, v105
	v_pk_fma_f32 v[98:99], v[98:99], v[188:189], v[130:131] op_sel_hi:[1,0,1]
	v_pk_mul_f32 v[104:105], v[106:107], v[110:111]
	v_pk_add_f32 v[106:107], v[112:113], 1.0 op_sel_hi:[1,0]
	v_pk_mul_f32 v[98:99], v[98:99], v[104:105]
	v_rcp_f32_e32 v106, v106
	v_rcp_f32_e32 v107, v107
	v_cvt_pk_bf16_f32 v104, v98, v99
	v_pk_fma_f32 v[98:99], v[100:101], v[188:189], v[132:133] op_sel_hi:[1,0,1]
	v_pk_fma_f32 v[94:95], v[94:95], v[186:187], v[142:143] op_sel_hi:[1,0,1]
	v_pk_mul_f32 v[100:101], v[108:109], v[106:107]
	v_pk_fma_f32 v[96:97], v[96:97], v[186:187], v[144:145] op_sel_hi:[1,0,1]
	v_pk_mul_f32 v[98:99], v[98:99], v[100:101]
	v_pk_mul_f32 v[100:101], v[94:95], s[84:85] op_sel_hi:[1,0]
	v_cvt_pk_bf16_f32 v105, v98, v99
	v_mad_i64_i32 v[98:99], s[20:21], v180, s72, v[114:115]
	v_exp_f32_e32 v100, v100
	v_exp_f32_e32 v101, v101
	v_lshl_add_u64 v[98:99], v[98:99], 0, s[18:19]
	v_lshl_add_u64 v[98:99], v[98:99], 0, s[36:37]
	v_lshl_add_u64 v[98:99], v[98:99], 0, v[116:117]
	global_store_dwordx4 v[98:99], v[102:105], off
	v_pk_add_f32 v[98:99], v[100:101], 1.0 op_sel_hi:[1,0]
	v_pk_mul_f32 v[100:101], v[96:97], s[84:85] op_sel_hi:[1,0]
	v_rcp_f32_e32 v98, v98
	v_rcp_f32_e32 v99, v99
	v_exp_f32_e32 v100, v100
	v_exp_f32_e32 v101, v101
	v_pk_fma_f32 v[86:87], v[86:87], v[186:187], v[138:139] op_sel_hi:[1,0,1]
	v_pk_mul_f32 v[94:95], v[94:95], v[98:99]
	v_pk_fma_f32 v[90:91], v[90:91], v[186:187], v[134:135] op_sel_hi:[1,0,1]
	v_pk_mul_f32 v[86:87], v[86:87], v[94:95]
	v_pk_add_f32 v[94:95], v[100:101], 1.0 op_sel_hi:[1,0]
	v_pk_mul_f32 v[98:99], v[90:91], s[84:85] op_sel_hi:[1,0]
	v_rcp_f32_e32 v94, v94
	v_rcp_f32_e32 v95, v95
	v_exp_f32_e32 v98, v98
	v_exp_f32_e32 v99, v99
	v_pk_fma_f32 v[88:89], v[88:89], v[186:187], v[140:141] op_sel_hi:[1,0,1]
	v_pk_mul_f32 v[94:95], v[96:97], v[94:95]
	v_pk_fma_f32 v[92:93], v[92:93], v[186:187], v[136:137] op_sel_hi:[1,0,1]
	v_pk_mul_f32 v[88:89], v[88:89], v[94:95]
	v_pk_add_f32 v[94:95], v[98:99], 1.0 op_sel_hi:[1,0]
	v_pk_mul_f32 v[96:97], v[92:93], s[84:85] op_sel_hi:[1,0]
	v_rcp_f32_e32 v94, v94
	v_rcp_f32_e32 v95, v95
	v_exp_f32_e32 v96, v96
	v_exp_f32_e32 v97, v97
	v_cvt_pk_bf16_f32 v86, v86, v87
	v_cvt_pk_bf16_f32 v87, v88, v89
	v_pk_mul_f32 v[88:89], v[90:91], v[94:95]
	v_pk_add_f32 v[90:91], v[96:97], 1.0 op_sel_hi:[1,0]
	v_pk_fma_f32 v[82:83], v[82:83], v[186:187], v[130:131] op_sel_hi:[1,0,1]
	v_rcp_f32_e32 v90, v90
	v_rcp_f32_e32 v91, v91
	v_pk_mul_f32 v[82:83], v[82:83], v[88:89]
	v_pk_fma_f32 v[78:79], v[78:79], v[182:183], v[142:143] op_sel_hi:[1,0,1]
	v_cvt_pk_bf16_f32 v88, v82, v83
	v_pk_fma_f32 v[82:83], v[84:85], v[186:187], v[132:133] op_sel_hi:[1,0,1]
	v_pk_mul_f32 v[84:85], v[92:93], v[90:91]
	v_pk_fma_f32 v[80:81], v[80:81], v[182:183], v[144:145] op_sel_hi:[1,0,1]
	v_pk_mul_f32 v[82:83], v[82:83], v[84:85]
	v_pk_mul_f32 v[84:85], v[78:79], s[84:85] op_sel_hi:[1,0]
	v_cvt_pk_bf16_f32 v89, v82, v83
	v_mad_i64_i32 v[82:83], s[20:21], v176, s72, v[114:115]
	v_exp_f32_e32 v84, v84
	v_exp_f32_e32 v85, v85
	v_lshl_add_u64 v[82:83], v[82:83], 0, s[18:19]
	v_lshl_add_u64 v[82:83], v[82:83], 0, s[36:37]
	v_lshl_add_u64 v[82:83], v[82:83], 0, v[116:117]
	global_store_dwordx4 v[82:83], v[86:89], off
	v_pk_add_f32 v[82:83], v[84:85], 1.0 op_sel_hi:[1,0]
	v_pk_mul_f32 v[84:85], v[80:81], s[84:85] op_sel_hi:[1,0]
	v_rcp_f32_e32 v82, v82
	v_rcp_f32_e32 v83, v83
	v_exp_f32_e32 v84, v84
	v_exp_f32_e32 v85, v85
	v_pk_fma_f32 v[70:71], v[70:71], v[182:183], v[138:139] op_sel_hi:[1,0,1]
	v_pk_mul_f32 v[78:79], v[78:79], v[82:83]
	v_pk_fma_f32 v[74:75], v[74:75], v[182:183], v[134:135] op_sel_hi:[1,0,1]
	v_pk_mul_f32 v[70:71], v[70:71], v[78:79]
	v_pk_add_f32 v[78:79], v[84:85], 1.0 op_sel_hi:[1,0]
	v_pk_mul_f32 v[82:83], v[74:75], s[84:85] op_sel_hi:[1,0]
	v_rcp_f32_e32 v78, v78
	v_rcp_f32_e32 v79, v79
	v_exp_f32_e32 v82, v82
	v_exp_f32_e32 v83, v83
	v_pk_fma_f32 v[72:73], v[72:73], v[182:183], v[140:141] op_sel_hi:[1,0,1]
	v_pk_mul_f32 v[78:79], v[80:81], v[78:79]
	v_pk_fma_f32 v[76:77], v[76:77], v[182:183], v[136:137] op_sel_hi:[1,0,1]
	v_pk_mul_f32 v[72:73], v[72:73], v[78:79]
	v_pk_add_f32 v[78:79], v[82:83], 1.0 op_sel_hi:[1,0]
	v_pk_mul_f32 v[80:81], v[76:77], s[84:85] op_sel_hi:[1,0]
	v_rcp_f32_e32 v78, v78
	v_rcp_f32_e32 v79, v79
	v_exp_f32_e32 v80, v80
	v_exp_f32_e32 v81, v81
	v_cvt_pk_bf16_f32 v70, v70, v71
	v_cvt_pk_bf16_f32 v71, v72, v73
	v_pk_mul_f32 v[72:73], v[74:75], v[78:79]
	v_pk_add_f32 v[74:75], v[80:81], 1.0 op_sel_hi:[1,0]
	v_pk_fma_f32 v[66:67], v[66:67], v[182:183], v[130:131] op_sel_hi:[1,0,1]
	v_rcp_f32_e32 v74, v74
	v_rcp_f32_e32 v75, v75
	v_pk_mul_f32 v[66:67], v[66:67], v[72:73]
	v_pk_fma_f32 v[62:63], v[62:63], v[178:179], v[142:143] op_sel_hi:[1,0,1]
	v_cvt_pk_bf16_f32 v72, v66, v67
	v_pk_fma_f32 v[66:67], v[68:69], v[182:183], v[132:133] op_sel_hi:[1,0,1]
	v_pk_mul_f32 v[68:69], v[76:77], v[74:75]
	v_pk_fma_f32 v[64:65], v[64:65], v[178:179], v[144:145] op_sel_hi:[1,0,1]
	v_pk_mul_f32 v[66:67], v[66:67], v[68:69]
	v_pk_mul_f32 v[68:69], v[62:63], s[84:85] op_sel_hi:[1,0]
	v_cvt_pk_bf16_f32 v73, v66, v67
	v_mad_i64_i32 v[66:67], s[20:21], v172, s72, v[114:115]
	v_exp_f32_e32 v68, v68
	v_exp_f32_e32 v69, v69
	v_lshl_add_u64 v[66:67], v[66:67], 0, s[18:19]
	v_lshl_add_u64 v[66:67], v[66:67], 0, s[36:37]
	v_lshl_add_u64 v[66:67], v[66:67], 0, v[116:117]
	global_store_dwordx4 v[66:67], v[70:73], off
	v_pk_add_f32 v[66:67], v[68:69], 1.0 op_sel_hi:[1,0]
	v_pk_mul_f32 v[68:69], v[64:65], s[84:85] op_sel_hi:[1,0]
	v_rcp_f32_e32 v66, v66
	v_rcp_f32_e32 v67, v67
	v_exp_f32_e32 v68, v68
	v_exp_f32_e32 v69, v69
	v_pk_fma_f32 v[54:55], v[54:55], v[178:179], v[138:139] op_sel_hi:[1,0,1]
	v_pk_mul_f32 v[62:63], v[62:63], v[66:67]
	v_pk_fma_f32 v[58:59], v[58:59], v[178:179], v[134:135] op_sel_hi:[1,0,1]
	v_pk_mul_f32 v[54:55], v[54:55], v[62:63]
	v_pk_add_f32 v[62:63], v[68:69], 1.0 op_sel_hi:[1,0]
	v_pk_mul_f32 v[66:67], v[58:59], s[84:85] op_sel_hi:[1,0]
	v_rcp_f32_e32 v62, v62
	v_rcp_f32_e32 v63, v63
	v_exp_f32_e32 v66, v66
	v_exp_f32_e32 v67, v67
	v_pk_fma_f32 v[56:57], v[56:57], v[178:179], v[140:141] op_sel_hi:[1,0,1]
	v_pk_mul_f32 v[62:63], v[64:65], v[62:63]
	v_pk_fma_f32 v[60:61], v[60:61], v[178:179], v[136:137] op_sel_hi:[1,0,1]
	v_pk_mul_f32 v[56:57], v[56:57], v[62:63]
	v_pk_add_f32 v[62:63], v[66:67], 1.0 op_sel_hi:[1,0]
	v_pk_mul_f32 v[64:65], v[60:61], s[84:85] op_sel_hi:[1,0]
	v_rcp_f32_e32 v62, v62
	v_rcp_f32_e32 v63, v63
	v_exp_f32_e32 v64, v64
	v_exp_f32_e32 v65, v65
	v_cvt_pk_bf16_f32 v54, v54, v55
	v_cvt_pk_bf16_f32 v55, v56, v57
	v_pk_mul_f32 v[56:57], v[58:59], v[62:63]
	v_pk_add_f32 v[58:59], v[64:65], 1.0 op_sel_hi:[1,0]
	v_pk_fma_f32 v[50:51], v[50:51], v[178:179], v[130:131] op_sel_hi:[1,0,1]
	v_rcp_f32_e32 v58, v58
	v_rcp_f32_e32 v59, v59
	v_pk_mul_f32 v[50:51], v[50:51], v[56:57]
	v_pk_fma_f32 v[46:47], v[46:47], v[174:175], v[142:143] op_sel_hi:[1,0,1]
	v_cvt_pk_bf16_f32 v56, v50, v51
	v_pk_fma_f32 v[50:51], v[52:53], v[178:179], v[132:133] op_sel_hi:[1,0,1]
	v_pk_mul_f32 v[52:53], v[60:61], v[58:59]
	v_pk_fma_f32 v[48:49], v[48:49], v[174:175], v[144:145] op_sel_hi:[1,0,1]
	v_pk_mul_f32 v[50:51], v[50:51], v[52:53]
	v_pk_mul_f32 v[52:53], v[46:47], s[84:85] op_sel_hi:[1,0]
	v_cvt_pk_bf16_f32 v57, v50, v51
	v_mad_i64_i32 v[50:51], s[20:21], v168, s72, v[114:115]
	v_exp_f32_e32 v52, v52
	v_exp_f32_e32 v53, v53
	v_lshl_add_u64 v[50:51], v[50:51], 0, s[18:19]
	v_lshl_add_u64 v[50:51], v[50:51], 0, s[36:37]
	v_lshl_add_u64 v[50:51], v[50:51], 0, v[116:117]
	global_store_dwordx4 v[50:51], v[54:57], off
	v_pk_add_f32 v[50:51], v[52:53], 1.0 op_sel_hi:[1,0]
	v_pk_mul_f32 v[52:53], v[48:49], s[84:85] op_sel_hi:[1,0]
	v_rcp_f32_e32 v50, v50
	v_rcp_f32_e32 v51, v51
	v_exp_f32_e32 v52, v52
	v_exp_f32_e32 v53, v53
	v_pk_fma_f32 v[38:39], v[38:39], v[174:175], v[138:139] op_sel_hi:[1,0,1]
	v_pk_mul_f32 v[46:47], v[46:47], v[50:51]
	v_pk_fma_f32 v[42:43], v[42:43], v[174:175], v[134:135] op_sel_hi:[1,0,1]
	v_pk_mul_f32 v[38:39], v[38:39], v[46:47]
	v_pk_add_f32 v[46:47], v[52:53], 1.0 op_sel_hi:[1,0]
	v_pk_mul_f32 v[50:51], v[42:43], s[84:85] op_sel_hi:[1,0]
	v_rcp_f32_e32 v46, v46
	v_rcp_f32_e32 v47, v47
	v_exp_f32_e32 v50, v50
	v_exp_f32_e32 v51, v51
	v_pk_fma_f32 v[40:41], v[40:41], v[174:175], v[140:141] op_sel_hi:[1,0,1]
	v_pk_mul_f32 v[46:47], v[48:49], v[46:47]
	v_pk_fma_f32 v[44:45], v[44:45], v[174:175], v[136:137] op_sel_hi:[1,0,1]
	v_pk_mul_f32 v[40:41], v[40:41], v[46:47]
	v_pk_add_f32 v[46:47], v[50:51], 1.0 op_sel_hi:[1,0]
	v_pk_mul_f32 v[48:49], v[44:45], s[84:85] op_sel_hi:[1,0]
	v_rcp_f32_e32 v46, v46
	v_rcp_f32_e32 v47, v47
	v_exp_f32_e32 v48, v48
	v_exp_f32_e32 v49, v49
	v_mov_b32_e32 v163, v161
	s_nop 1
	v_permlane32_swap_b32_e32 v161, v163
	v_add_f32_e32 v161, v161, v163
	v_fmamk_f32 v161, v161, 0x3a800000, v244
	v_cvt_pk_bf16_f32 v38, v38, v39
	v_cvt_pk_bf16_f32 v39, v40, v41
	v_pk_mul_f32 v[40:41], v[42:43], v[46:47]
	v_pk_add_f32 v[42:43], v[48:49], 1.0 op_sel_hi:[1,0]
	v_rsq_f32_e32 v170, v161
	v_rcp_f32_e32 v42, v42
	v_rcp_f32_e32 v43, v43
	v_pk_fma_f32 v[34:35], v[34:35], v[174:175], v[130:131] op_sel_hi:[1,0,1]
	v_pk_fma_f32 v[30:31], v[30:31], v[170:171], v[142:143] op_sel_hi:[1,0,1]
	v_pk_mul_f32 v[34:35], v[34:35], v[40:41]
	v_pk_fma_f32 v[32:33], v[32:33], v[170:171], v[144:145] op_sel_hi:[1,0,1]
	v_cvt_pk_bf16_f32 v40, v34, v35
	v_pk_fma_f32 v[34:35], v[36:37], v[174:175], v[132:133] op_sel_hi:[1,0,1]
	v_pk_mul_f32 v[36:37], v[44:45], v[42:43]
	v_pk_fma_f32 v[22:23], v[22:23], v[170:171], v[138:139] op_sel_hi:[1,0,1]
	v_pk_mul_f32 v[34:35], v[34:35], v[36:37]
	v_pk_mul_f32 v[36:37], v[30:31], s[84:85] op_sel_hi:[1,0]
	v_cvt_pk_bf16_f32 v41, v34, v35
	v_mad_i64_i32 v[34:35], s[20:21], v164, s72, v[114:115]
	v_exp_f32_e32 v36, v36
	v_exp_f32_e32 v37, v37
	v_lshl_add_u64 v[34:35], v[34:35], 0, s[18:19]
	v_lshl_add_u64 v[34:35], v[34:35], 0, s[36:37]
	v_lshl_add_u64 v[34:35], v[34:35], 0, v[116:117]
	global_store_dwordx4 v[34:35], v[38:41], off
	v_pk_add_f32 v[34:35], v[36:37], 1.0 op_sel_hi:[1,0]
	v_pk_mul_f32 v[36:37], v[32:33], s[84:85] op_sel_hi:[1,0]
	v_rcp_f32_e32 v34, v34
	v_rcp_f32_e32 v35, v35
	v_exp_f32_e32 v36, v36
	v_exp_f32_e32 v37, v37
	v_pk_fma_f32 v[26:27], v[26:27], v[170:171], v[134:135] op_sel_hi:[1,0,1]
	v_pk_mul_f32 v[30:31], v[30:31], v[34:35]
	v_pk_mul_f32 v[34:35], v[26:27], s[84:85] op_sel_hi:[1,0]
	v_pk_mul_f32 v[22:23], v[22:23], v[30:31]
	v_pk_add_f32 v[30:31], v[36:37], 1.0 op_sel_hi:[1,0]
	ds_swizzle_b32 v166, v165 offset:swizzle(SWAP,16)
	v_rcp_f32_e32 v30, v30
	v_rcp_f32_e32 v31, v31
	v_exp_f32_e32 v34, v34
	v_exp_f32_e32 v35, v35
	v_pk_fma_f32 v[24:25], v[24:25], v[170:171], v[140:141] op_sel_hi:[1,0,1]
	v_pk_mul_f32 v[30:31], v[32:33], v[30:31]
	v_pk_fma_f32 v[28:29], v[28:29], v[170:171], v[136:137] op_sel_hi:[1,0,1]
	v_pk_mul_f32 v[24:25], v[24:25], v[30:31]
	v_pk_add_f32 v[30:31], v[34:35], 1.0 op_sel_hi:[1,0]
	v_pk_mul_f32 v[32:33], v[28:29], s[84:85] op_sel_hi:[1,0]
	s_waitcnt lgkmcnt(0)
	v_add_f32_e32 v161, v165, v166
	v_rcp_f32_e32 v30, v30
	v_rcp_f32_e32 v31, v31
	v_exp_f32_e32 v32, v32
	v_exp_f32_e32 v33, v33
	v_mov_b32_e32 v163, v161
	s_nop 1
	v_permlane32_swap_b32_e32 v161, v163
	v_add_f32_e32 v161, v161, v163
	v_fmamk_f32 v161, v161, 0x3a800000, v244
	v_cvt_pk_bf16_f32 v22, v22, v23
	v_cvt_pk_bf16_f32 v23, v24, v25
	v_pk_mul_f32 v[24:25], v[26:27], v[30:31]
	v_pk_add_f32 v[26:27], v[32:33], 1.0 op_sel_hi:[1,0]
	v_rsq_f32_e32 v166, v161
	v_rcp_f32_e32 v26, v26
	v_rcp_f32_e32 v27, v27
	v_pk_fma_f32 v[18:19], v[18:19], v[170:171], v[130:131] op_sel_hi:[1,0,1]
	v_pk_fma_f32 v[14:15], v[14:15], v[166:167], v[142:143] op_sel_hi:[1,0,1]
	v_pk_mul_f32 v[18:19], v[18:19], v[24:25]
	v_pk_fma_f32 v[16:17], v[16:17], v[166:167], v[144:145] op_sel_hi:[1,0,1]
	v_cvt_pk_bf16_f32 v24, v18, v19
	v_pk_fma_f32 v[18:19], v[20:21], v[170:171], v[132:133] op_sel_hi:[1,0,1]
	v_pk_mul_f32 v[20:21], v[28:29], v[26:27]
	v_pk_fma_f32 v[6:7], v[6:7], v[166:167], v[138:139] op_sel_hi:[1,0,1]
	v_pk_mul_f32 v[18:19], v[18:19], v[20:21]
	v_pk_mul_f32 v[20:21], v[14:15], s[84:85] op_sel_hi:[1,0]
	v_cvt_pk_bf16_f32 v25, v18, v19
	v_mad_i64_i32 v[18:19], s[20:21], v162, s72, v[114:115]
	v_exp_f32_e32 v20, v20
	v_exp_f32_e32 v21, v21
	v_lshl_add_u64 v[18:19], v[18:19], 0, s[18:19]
	v_lshl_add_u64 v[18:19], v[18:19], 0, s[36:37]
	v_lshl_add_u64 v[18:19], v[18:19], 0, v[116:117]
	global_store_dwordx4 v[18:19], v[22:25], off
	v_pk_add_f32 v[18:19], v[20:21], 1.0 op_sel_hi:[1,0]
	v_pk_mul_f32 v[20:21], v[16:17], s[84:85] op_sel_hi:[1,0]
	v_rcp_f32_e32 v18, v18
	v_rcp_f32_e32 v19, v19
	v_exp_f32_e32 v20, v20
	v_exp_f32_e32 v21, v21
	v_pk_fma_f32 v[10:11], v[10:11], v[166:167], v[134:135] op_sel_hi:[1,0,1]
	v_pk_mul_f32 v[14:15], v[14:15], v[18:19]
	v_pk_mul_f32 v[18:19], v[10:11], s[84:85] op_sel_hi:[1,0]
	v_pk_mul_f32 v[6:7], v[6:7], v[14:15]
	v_pk_add_f32 v[14:15], v[20:21], 1.0 op_sel_hi:[1,0]
	v_exp_f32_e32 v18, v18
	v_rcp_f32_e32 v14, v14
	v_rcp_f32_e32 v15, v15
	v_exp_f32_e32 v19, v19
	v_pk_fma_f32 v[8:9], v[8:9], v[166:167], v[140:141] op_sel_hi:[1,0,1]
	v_pk_fma_f32 v[12:13], v[12:13], v[166:167], v[136:137] op_sel_hi:[1,0,1]
	v_pk_mul_f32 v[14:15], v[16:17], v[14:15]
	v_pk_mul_f32 v[16:17], v[12:13], s[84:85] op_sel_hi:[1,0]
	v_pk_mul_f32 v[8:9], v[8:9], v[14:15]
	v_pk_add_f32 v[14:15], v[18:19], 1.0 op_sel_hi:[1,0]
	v_exp_f32_e32 v16, v16
	v_rcp_f32_e32 v14, v14
	v_rcp_f32_e32 v15, v15
	v_exp_f32_e32 v17, v17
	v_cvt_pk_bf16_f32 v6, v6, v7
	v_cvt_pk_bf16_f32 v7, v8, v9
	v_pk_mul_f32 v[8:9], v[10:11], v[14:15]
	v_pk_add_f32 v[10:11], v[16:17], 1.0 op_sel_hi:[1,0]
	v_pk_fma_f32 v[2:3], v[2:3], v[166:167], v[130:131] op_sel_hi:[1,0,1]
	v_rcp_f32_e32 v10, v10
	v_rcp_f32_e32 v11, v11
	v_pk_mul_f32 v[2:3], v[2:3], v[8:9]
	s_nop 0
	v_cvt_pk_bf16_f32 v8, v2, v3
	v_pk_fma_f32 v[2:3], v[4:5], v[166:167], v[132:133] op_sel_hi:[1,0,1]
	v_pk_mul_f32 v[4:5], v[12:13], v[10:11]
	s_nop 0
	v_pk_mul_f32 v[2:3], v[2:3], v[4:5]
	s_nop 0
	v_cvt_pk_bf16_f32 v9, v2, v3
	v_mad_i64_i32 v[2:3], s[20:21], v160, s72, v[114:115]
	v_lshl_add_u64 v[2:3], v[2:3], 0, s[18:19]
	v_lshl_add_u64 v[2:3], v[2:3], 0, s[36:37]
	v_lshl_add_u64 v[2:3], v[2:3], 0, v[116:117]
	global_store_dwordx4 v[2:3], v[6:9], off
	s_cbranch_vccnz .LBB0_1244
	s_andn2_b64 vcc, exec, s[2:3]
	s_cbranch_vccnz .LBB0_1243
	s_barrier
	s_branch .LBB0_1243

.LBB0_1336:
	s_andn2_b64 vcc, exec, s[10:11]
	s_cmp_lg_u32 s35, 0
	s_cselect_b64 s[12:13], -1, 0
	s_lshl_b64 s[8:9], s[8:9], 2
	s_add_u32 s8, s66, s8
	s_addc_u32 s9, s67, s9
	s_lshl_b32 s31, s34, 8
	s_add_i32 s31, s31, s0
	v_or_b32_e32 v200, s31, v206
	v_ashrrev_i32_e32 v201, 31, v200
	v_lshlrev_b64 v[4:5], 6, v[200:201]
	v_lshl_add_u64 v[24:25], v[184:185], 0, v[4:5]
	global_load_dwordx4 v[4:7], v[24:25], off
	v_or_b32_e32 v198, 16, v200
	v_ashrrev_i32_e32 v199, 31, v198
	v_lshlrev_b64 v[8:9], 6, v[198:199]
	v_lshl_add_u64 v[8:9], v[184:185], 0, v[8:9]
	global_load_dwordx4 v[8:11], v[8:9], off
	v_or_b32_e32 v196, 32, v200
	v_ashrrev_i32_e32 v197, 31, v196
	v_lshlrev_b64 v[12:13], 6, v[196:197]
	v_lshl_add_u64 v[12:13], v[184:185], 0, v[12:13]
	global_load_dwordx4 v[12:15], v[12:13], off
	v_or_b32_e32 v194, 48, v200
	v_ashrrev_i32_e32 v195, 31, v194
	v_lshlrev_b64 v[16:17], 6, v[194:195]
	v_lshl_add_u64 v[16:17], v[184:185], 0, v[16:17]
	global_load_dwordx4 v[16:19], v[16:17], off
	v_add_u32_e32 v192, 0x80, v200
	v_ashrrev_i32_e32 v193, 31, v192
	v_lshlrev_b64 v[20:21], 6, v[192:193]
	v_lshl_add_u64 v[20:21], v[184:185], 0, v[20:21]
	global_load_dwordx4 v[20:23], v[20:21], off
	v_add_co_u32_e32 v32, vcc, s59, v24
	v_lshl_add_u32 v190, s33, 8, v208
	s_nop 0
	v_addc_co_u32_e32 v33, vcc, 0, v25, vcc
	global_load_dwordx4 v[24:27], v[32:33], off offset:1024
	global_load_dwordx4 v[28:31], v[32:33], off offset:2048
	global_load_dwordx4 v[66:69], v[32:33], off offset:3072
	v_ashrrev_i32_e32 v191, 31, v190
	v_lshl_add_u64 v[2:3], v[190:191], 2, s[8:9]
	s_and_b64 s[10:11], s[6:7], s[12:13]
	s_andn2_b64 vcc, exec, s[10:11]
	s_waitcnt vmcnt(0)
	v_add_f32_e32 v4, v4, v5
	v_add_f32_e32 v5, v6, v7
	v_add_f32_e32 v4, v4, v5
	s_waitcnt lgkmcnt(0)
	v_mov_b32_e32 v5, v4
	s_nop 1
	v_permlane16_swap_b32_e32 v4, v5
	v_add_f32_e32 v197, v4, v5
	v_add_f32_e32 v4, v8, v9
	v_add_f32_e32 v5, v10, v11
	v_add_f32_e32 v4, v4, v5
	v_mov_b32_e32 v202, v197
	s_nop 1
	v_permlane32_swap_b32_e32 v197, v202
	s_waitcnt lgkmcnt(0)
	v_mov_b32_e32 v5, v4
	s_nop 1
	v_permlane16_swap_b32_e32 v4, v5
	v_add_f32_e32 v222, v4, v5
	v_add_f32_e32 v4, v12, v13
	v_add_f32_e32 v5, v14, v15
	v_add_f32_e32 v4, v4, v5
	v_mov_b32_e32 v223, v222
	s_nop 1
	v_permlane32_swap_b32_e32 v222, v223
	s_waitcnt lgkmcnt(0)
	v_mov_b32_e32 v5, v4
	s_nop 1
	v_permlane16_swap_b32_e32 v4, v5
	v_add_f32_e32 v220, v4, v5
	v_add_f32_e32 v4, v16, v17
	v_add_f32_e32 v5, v18, v19
	v_add_f32_e32 v4, v4, v5
	v_mov_b32_e32 v221, v220
	s_nop 1
	v_permlane32_swap_b32_e32 v220, v221
	s_waitcnt lgkmcnt(0)
	v_mov_b32_e32 v5, v4
	s_nop 1
	v_permlane16_swap_b32_e32 v4, v5
	v_add_f32_e32 v218, v4, v5
	v_add_f32_e32 v4, v20, v21
	v_add_f32_e32 v5, v22, v23
	v_add_f32_e32 v4, v4, v5
	v_mov_b32_e32 v219, v218
	s_nop 1
	v_permlane32_swap_b32_e32 v218, v219
	s_waitcnt lgkmcnt(0)
	v_mov_b32_e32 v5, v4
	s_nop 1
	v_permlane16_swap_b32_e32 v4, v5
	v_add_f32_e32 v216, v4, v5
	v_add_f32_e32 v4, v24, v25
	v_add_f32_e32 v5, v26, v27
	v_add_f32_e32 v4, v4, v5
	v_mov_b32_e32 v217, v216
	s_nop 1
	v_permlane32_swap_b32_e32 v216, v217
	s_waitcnt lgkmcnt(0)
	v_mov_b32_e32 v5, v4
	s_nop 1
	v_permlane16_swap_b32_e32 v4, v5
	v_add_f32_e32 v214, v4, v5
	v_add_f32_e32 v4, v28, v29
	v_add_f32_e32 v5, v30, v31
	v_add_f32_e32 v4, v4, v5
	v_mov_b32_e32 v215, v214
	s_nop 1
	v_permlane32_swap_b32_e32 v214, v215
	s_waitcnt lgkmcnt(0)
	v_mov_b32_e32 v5, v4
	s_nop 1
	v_permlane16_swap_b32_e32 v4, v5
	v_add_f32_e32 v199, v4, v5
	v_add_f32_e32 v4, v66, v67
	v_add_f32_e32 v5, v68, v69
	global_load_dwordx4 v[82:85], v[2:3], off offset:16
	global_load_dwordx4 v[86:89], v[2:3], off
	global_load_dwordx4 v[66:69], v[2:3], off offset:528
	global_load_dwordx4 v[70:73], v[2:3], off offset:512
	v_add_f32_e32 v4, v4, v5
	ds_swizzle_b32 v5, v4 offset:swizzle(SWAP,16)
	v_mov_b32_e32 v201, v199
	v_cndmask_b32_e64 v2, 0, 1, s[10:11]
	s_nop 0
	v_permlane32_swap_b32_e32 v199, v201
	s_waitcnt lgkmcnt(0)
	v_add_f32_e32 v193, v4, v5
	v_mov_b32_e32 v195, v193
	s_nop 1
	v_permlane32_swap_b32_e32 v193, v195
	v_cmp_ne_u32_e64 s[14:15], 1, v2
	s_cbranch_vccnz .LBB0_1338
	s_bfe_u32 s8, s31, 0x50006
	v_mov_b32_e32 v2, s8
	v_cndmask_b32_e64 v2, v206, v2, s[2:3]
	v_lshlrev_b32_e32 v3, 2, v209
	v_lshl_or_b32 v2, v2, 7, v3
	global_load_dwordx4 v[14:17], v2, s[26:27] offset:48
	global_load_dwordx4 v[10:13], v2, s[26:27] offset:32
	global_load_dwordx4 v[6:9], v2, s[26:27] offset:16
	s_nop 0
	global_load_dwordx4 v[2:5], v2, s[26:27]

.LBB0_1458:
	v_mul_f32_e32 v134, v134, v134
	v_mul_f32_e32 v142, v142, v142
	v_fmac_f32_e32 v134, v135, v135
	v_mul_f32_e32 v135, v136, v136
	v_fmac_f32_e32 v142, v143, v143
	v_mul_f32_e32 v143, v144, v144
	v_fmac_f32_e32 v135, v137, v137
	v_mul_f32_e32 v131, v131, v131
	v_fmac_f32_e32 v143, v145, v145
	v_mul_f32_e32 v138, v138, v138
	v_add_f32_e32 v134, v135, v134
	v_fmac_f32_e32 v131, v130, v130
	v_add_f32_e32 v142, v143, v142
	v_fmac_f32_e32 v138, v139, v139
	v_mul_f32_e32 v139, v140, v140
	v_add_f32_e32 v130, v134, v131
	v_mul_f32_e32 v131, v132, v132
	v_add_f32_e32 v138, v142, v138
	v_fmac_f32_e32 v139, v141, v141
	v_fmac_f32_e32 v131, v133, v133
	v_add_f32_e32 v138, v139, v138
	v_add_f32_e32 v130, v131, v130
	v_add_f32_e32 v130, v138, v130
	s_lshl_b32 s30, s36, 2
	s_ashr_i32 s31, s30, 31
	s_waitcnt lgkmcnt(0)
	v_mov_b32_e32 v131, v130
	s_nop 1
	v_permlane16_swap_b32_e32 v130, v131
	v_add_f32_e32 v130, v130, v131
	v_mov_b32_e32 v131, v130
	s_nop 1
	v_permlane32_swap_b32_e32 v130, v131
	s_and_saveexec_b64 s[38:39], s[2:3]
	s_cbranch_execz .LBB0_1460
	v_lshlrev_b64 v[132:133], 6, v[192:193]
	v_lshl_add_u64 v[132:133], s[18:19], 0, v[132:133]
	v_lshl_add_u64 v[132:133], s[30:31], 2, v[132:133]
	s_lshl_b32 s36, s58, 2
	v_lshl_add_u64 v[132:133], v[132:133], 0, s[36:37]
	v_add_f32_e32 v130, v130, v131
	global_store_dword v[132:133], v130, off

.LBB0_1464:
	v_mul_f32_e32 v126, v126, v126
	v_mul_f32_e32 v118, v118, v118
	v_fmac_f32_e32 v126, v127, v127
	v_mul_f32_e32 v127, v128, v128
	v_fmac_f32_e32 v118, v119, v119
	v_mul_f32_e32 v119, v120, v120
	v_fmac_f32_e32 v127, v129, v129
	v_mul_f32_e32 v123, v123, v123
	v_fmac_f32_e32 v119, v121, v121
	v_mul_f32_e32 v115, v115, v115
	v_add_f32_e32 v126, v127, v126
	v_fmac_f32_e32 v123, v122, v122
	v_add_f32_e32 v118, v119, v118
	v_fmac_f32_e32 v115, v114, v114
	v_add_f32_e32 v122, v126, v123
	v_mul_f32_e32 v123, v124, v124
	v_add_f32_e32 v114, v118, v115
	v_mul_f32_e32 v115, v116, v116
	v_fmac_f32_e32 v123, v125, v125
	v_fmac_f32_e32 v115, v117, v117
	v_add_f32_e32 v122, v123, v122
	v_add_f32_e32 v114, v115, v114
	v_add_f32_e32 v114, v122, v114
	s_waitcnt lgkmcnt(0)
	v_mov_b32_e32 v115, v114
	s_nop 1
	v_permlane16_swap_b32_e32 v114, v115
	v_add_f32_e32 v114, v114, v115
	v_mov_b32_e32 v115, v114
	s_nop 1
	v_permlane32_swap_b32_e32 v114, v115
	s_and_saveexec_b64 s[38:39], s[2:3]
	s_cbranch_execz .LBB0_1466
	v_lshlrev_b64 v[116:117], 6, v[138:139]
	v_lshl_add_u64 v[116:117], s[18:19], 0, v[116:117]
	v_lshl_add_u64 v[116:117], s[30:31], 2, v[116:117]
	s_lshl_b32 s36, s58, 2
	v_lshl_add_u64 v[116:117], v[116:117], 0, s[36:37]
	v_add_f32_e32 v114, v114, v115
	global_store_dword v[116:117], v114, off

.LBB0_1470:
	v_mul_f32_e32 v110, v110, v110
	v_mul_f32_e32 v102, v102, v102
	v_fmac_f32_e32 v110, v111, v111
	v_mul_f32_e32 v111, v112, v112
	v_fmac_f32_e32 v102, v103, v103
	v_mul_f32_e32 v103, v104, v104
	v_fmac_f32_e32 v111, v113, v113
	v_mul_f32_e32 v107, v107, v107
	v_fmac_f32_e32 v103, v105, v105
	v_mul_f32_e32 v99, v99, v99
	v_add_f32_e32 v110, v111, v110
	v_fmac_f32_e32 v107, v106, v106
	v_add_f32_e32 v102, v103, v102
	v_fmac_f32_e32 v99, v98, v98
	v_add_f32_e32 v106, v107, v110
	v_mul_f32_e32 v107, v108, v108
	v_add_f32_e32 v98, v99, v102
	v_mul_f32_e32 v99, v100, v100
	v_fmac_f32_e32 v107, v109, v109
	v_fmac_f32_e32 v99, v101, v101
	v_add_f32_e32 v106, v107, v106
	v_add_f32_e32 v98, v99, v98
	v_add_f32_e32 v98, v106, v98
	s_waitcnt lgkmcnt(0)
	v_mov_b32_e32 v99, v98
	s_nop 1
	v_permlane16_swap_b32_e32 v98, v99
	v_add_f32_e32 v98, v98, v99
	v_mov_b32_e32 v99, v98
	s_nop 1
	v_permlane32_swap_b32_e32 v98, v99
	s_and_saveexec_b64 s[38:39], s[2:3]
	s_cbranch_execz .LBB0_1472
	v_lshlrev_b64 v[100:101], 6, v[122:123]
	v_lshl_add_u64 v[100:101], s[18:19], 0, v[100:101]
	v_lshl_add_u64 v[100:101], s[30:31], 2, v[100:101]
	s_lshl_b32 s36, s58, 2
	v_lshl_add_u64 v[100:101], v[100:101], 0, s[36:37]
	v_add_f32_e32 v98, v98, v99
	global_store_dword v[100:101], v98, off

.LBB0_1476:
	v_mul_f32_e32 v94, v94, v94
	v_mul_f32_e32 v86, v86, v86
	v_fmac_f32_e32 v94, v95, v95
	v_mul_f32_e32 v95, v96, v96
	v_fmac_f32_e32 v86, v87, v87
	v_mul_f32_e32 v87, v88, v88
	v_fmac_f32_e32 v95, v97, v97
	v_mul_f32_e32 v91, v91, v91
	v_fmac_f32_e32 v87, v89, v89
	v_mul_f32_e32 v83, v83, v83
	v_add_f32_e32 v94, v95, v94
	v_fmac_f32_e32 v91, v90, v90
	v_add_f32_e32 v86, v87, v86
	v_fmac_f32_e32 v83, v82, v82
	v_add_f32_e32 v90, v91, v94
	v_mul_f32_e32 v91, v92, v92
	v_add_f32_e32 v82, v83, v86
	v_mul_f32_e32 v83, v84, v84
	v_fmac_f32_e32 v91, v93, v93
	v_fmac_f32_e32 v83, v85, v85
	v_add_f32_e32 v90, v91, v90
	v_add_f32_e32 v82, v83, v82
	v_add_f32_e32 v82, v82, v90
	s_waitcnt lgkmcnt(0)
	v_mov_b32_e32 v83, v82
	s_nop 1
	v_permlane16_swap_b32_e32 v82, v83
	v_add_f32_e32 v82, v82, v83
	v_mov_b32_e32 v83, v82
	s_nop 1
	v_permlane32_swap_b32_e32 v82, v83
	s_and_saveexec_b64 s[38:39], s[2:3]
	s_cbranch_execz .LBB0_1478
	v_lshlrev_b64 v[84:85], 6, v[106:107]
	v_lshl_add_u64 v[84:85], s[18:19], 0, v[84:85]
	v_lshl_add_u64 v[84:85], s[30:31], 2, v[84:85]
	s_lshl_b32 s36, s58, 2
	v_lshl_add_u64 v[84:85], v[84:85], 0, s[36:37]
	v_add_f32_e32 v82, v82, v83
	global_store_dword v[84:85], v82, off

.LBB0_1482:
	v_mul_f32_e32 v62, v62, v62
	v_mul_f32_e32 v54, v54, v54
	v_fmac_f32_e32 v62, v63, v63
	v_mul_f32_e32 v63, v64, v64
	v_fmac_f32_e32 v54, v55, v55
	v_mul_f32_e32 v55, v56, v56
	v_fmac_f32_e32 v63, v65, v65
	v_mul_f32_e32 v59, v59, v59
	v_fmac_f32_e32 v55, v57, v57
	v_mul_f32_e32 v51, v51, v51
	v_add_f32_e32 v62, v63, v62
	v_fmac_f32_e32 v59, v58, v58
	v_add_f32_e32 v54, v55, v54
	v_fmac_f32_e32 v51, v50, v50
	v_add_f32_e32 v58, v59, v62
	v_mul_f32_e32 v59, v60, v60
	v_add_f32_e32 v50, v51, v54
	v_mul_f32_e32 v51, v52, v52
	v_fmac_f32_e32 v59, v61, v61
	v_fmac_f32_e32 v51, v53, v53
	v_add_f32_e32 v58, v59, v58
	v_add_f32_e32 v50, v51, v50
	v_add_f32_e32 v50, v58, v50
	s_waitcnt lgkmcnt(0)
	v_mov_b32_e32 v51, v50
	s_nop 1
	v_permlane16_swap_b32_e32 v50, v51
	v_add_f32_e32 v50, v50, v51
	v_mov_b32_e32 v51, v50
	s_nop 1
	v_permlane32_swap_b32_e32 v50, v51
	s_and_saveexec_b64 s[38:39], s[2:3]
	s_cbranch_execz .LBB0_1484
	v_lshlrev_b64 v[52:53], 6, v[90:91]
	v_lshl_add_u64 v[52:53], s[18:19], 0, v[52:53]
	v_lshl_add_u64 v[52:53], s[30:31], 2, v[52:53]
	s_lshl_b32 s36, s58, 2
	v_lshl_add_u64 v[52:53], v[52:53], 0, s[36:37]
	v_add_f32_e32 v50, v50, v51
	global_store_dword v[52:53], v50, off

.LBB0_1488:
	v_mul_f32_e32 v46, v46, v46
	v_mul_f32_e32 v38, v38, v38
	v_fmac_f32_e32 v46, v47, v47
	v_mul_f32_e32 v47, v48, v48
	v_fmac_f32_e32 v38, v39, v39
	v_mul_f32_e32 v39, v40, v40
	v_fmac_f32_e32 v47, v49, v49
	v_mul_f32_e32 v43, v43, v43
	v_fmac_f32_e32 v39, v41, v41
	v_mul_f32_e32 v35, v35, v35
	v_add_f32_e32 v46, v47, v46
	v_fmac_f32_e32 v43, v42, v42
	v_add_f32_e32 v38, v39, v38
	v_fmac_f32_e32 v35, v34, v34
	v_add_f32_e32 v42, v43, v46
	v_mul_f32_e32 v43, v44, v44
	v_add_f32_e32 v34, v35, v38
	v_mul_f32_e32 v35, v36, v36
	v_fmac_f32_e32 v43, v45, v45
	v_fmac_f32_e32 v35, v37, v37
	v_add_f32_e32 v42, v43, v42
	v_add_f32_e32 v34, v35, v34
	v_add_f32_e32 v34, v34, v42
	s_waitcnt lgkmcnt(0)
	v_mov_b32_e32 v35, v34
	s_nop 1
	v_permlane16_swap_b32_e32 v34, v35
	v_add_f32_e32 v34, v34, v35
	v_mov_b32_e32 v35, v34
	s_nop 1
	v_permlane32_swap_b32_e32 v34, v35
	s_and_saveexec_b64 s[38:39], s[2:3]
	s_cbranch_execz .LBB0_1490
	v_lshlrev_b64 v[36:37], 6, v[58:59]
	v_lshl_add_u64 v[36:37], s[18:19], 0, v[36:37]
	v_lshl_add_u64 v[36:37], s[30:31], 2, v[36:37]
	s_lshl_b32 s36, s58, 2
	v_lshl_add_u64 v[36:37], v[36:37], 0, s[36:37]
	v_add_f32_e32 v34, v34, v35
	global_store_dword v[36:37], v34, off

.LBB0_1494:
	v_mul_f32_e32 v30, v30, v30
	v_mul_f32_e32 v22, v22, v22
	v_fmac_f32_e32 v30, v31, v31
	v_mul_f32_e32 v31, v32, v32
	v_fmac_f32_e32 v22, v23, v23
	v_mul_f32_e32 v23, v24, v24
	v_fmac_f32_e32 v31, v33, v33
	v_mul_f32_e32 v27, v27, v27
	v_fmac_f32_e32 v23, v25, v25
	v_mul_f32_e32 v19, v19, v19
	v_add_f32_e32 v30, v31, v30
	v_fmac_f32_e32 v27, v26, v26
	v_add_f32_e32 v22, v23, v22
	v_fmac_f32_e32 v19, v18, v18
	v_add_f32_e32 v26, v27, v30
	v_mul_f32_e32 v27, v28, v28
	v_add_f32_e32 v18, v19, v22
	v_mul_f32_e32 v19, v20, v20
	v_fmac_f32_e32 v27, v29, v29
	v_fmac_f32_e32 v19, v21, v21
	v_add_f32_e32 v26, v27, v26
	v_add_f32_e32 v18, v19, v18
	v_add_f32_e32 v18, v26, v18
	s_waitcnt lgkmcnt(0)
	v_mov_b32_e32 v19, v18
	s_nop 1
	v_permlane16_swap_b32_e32 v18, v19
	v_add_f32_e32 v18, v18, v19
	v_mov_b32_e32 v19, v18
	s_nop 1
	v_permlane32_swap_b32_e32 v18, v19
	s_and_saveexec_b64 s[38:39], s[2:3]
	s_cbranch_execz .LBB0_1496
	v_lshlrev_b64 v[20:21], 6, v[34:35]
	v_lshl_add_u64 v[20:21], s[18:19], 0, v[20:21]
	v_lshl_add_u64 v[20:21], s[30:31], 2, v[20:21]
	s_lshl_b32 s36, s58, 2
	v_lshl_add_u64 v[20:21], v[20:21], 0, s[36:37]
	v_add_f32_e32 v18, v18, v19
	global_store_dword v[20:21], v18, off

.LBB0_1500:
	v_mul_f32_e32 v14, v14, v14
	v_mul_f32_e32 v6, v6, v6
	v_fmac_f32_e32 v14, v15, v15
	v_mul_f32_e32 v15, v16, v16
	v_fmac_f32_e32 v6, v7, v7
	v_mul_f32_e32 v7, v8, v8
	v_fmac_f32_e32 v15, v17, v17
	v_mul_f32_e32 v11, v11, v11
	v_fmac_f32_e32 v7, v9, v9
	v_mul_f32_e32 v3, v3, v3
	v_add_f32_e32 v14, v15, v14
	v_fmac_f32_e32 v11, v10, v10
	v_add_f32_e32 v6, v7, v6
	v_fmac_f32_e32 v3, v2, v2
	v_add_f32_e32 v10, v11, v14
	v_mul_f32_e32 v11, v12, v12
	v_add_f32_e32 v2, v3, v6
	v_mul_f32_e32 v3, v4, v4
	v_fmac_f32_e32 v11, v13, v13
	v_fmac_f32_e32 v3, v5, v5
	v_add_f32_e32 v10, v11, v10
	v_add_f32_e32 v2, v3, v2
	v_add_f32_e32 v2, v2, v10
	s_waitcnt lgkmcnt(0)
	v_mov_b32_e32 v3, v2
	s_nop 1
	v_permlane16_swap_b32_e32 v2, v3
	v_add_f32_e32 v2, v2, v3
	v_mov_b32_e32 v3, v2
	s_nop 1
	v_permlane32_swap_b32_e32 v2, v3
	s_and_saveexec_b64 s[6:7], s[2:3]
	s_cbranch_execz .LBB0_1502
	v_lshlrev_b64 v[4:5], 6, v[18:19]
	v_lshl_add_u64 v[4:5], s[18:19], 0, v[4:5]
	v_lshl_add_u64 v[4:5], s[30:31], 2, v[4:5]
	s_lshl_b32 s36, s58, 2
	v_lshl_add_u64 v[4:5], v[4:5], 0, s[36:37]
	v_add_f32_e32 v2, v2, v3
	global_store_dword v[4:5], v2, off
